# rstd-table fill loops: four units' loads in flight per iteration, one wait, instead of a round trip per unit
# baseline (speedup 1.0000x reference)
; __device__ __forceinline__ int opaque_tid() { int t = threadIdx.x; asm volatile("" : "+v"(t)); return t; }
; #define LAS __attribute__((address_space(3)))
; template <class Sched> __device__ __forceinline__ void fill_rtab(LAS float* rtab, const Sched& S, const float* ss) {
;     pg8::Unit u; const int tix = pg8::opaque_tid();
; #pragma unroll 4
;     for (int i = 0; S.next(i, u) && i < 12; ++i) { if (tix < 256) { const f32x4* p = (const f32x4*)(ss + (size_t)(u.pm * 256 + tix) * 16);
;             const f32x4 a = p[0], b = p[1], c = p[2], d = p[3]; const float t = ((a[0] + a[1]) + (a[2] + a[3])) + ((b[0] + b[1]) + (b[2] + b[3])) + ((c[0] + c[1]) + (c[2] + c[3])) + ((d[0] + d[1]) + (d[2] + d[3]));
;             rtab[i * 256 + tix] = __builtin_amdgcn_rsqf(t * (1.0f / 1024.0f) + 1e-6f); } }
;     __syncthreads();
; }
.LBB0_295:
	s_or_b64 exec, exec, s[0:1]
	s_mov_b64 s[0:1], 0
.LBB0_296:
	s_cmp_eq_u32 s28, 0
	s_cbranch_scc1 .Lrt0_done
	s_and_saveexec_b64 s[40:41], s[4:5]
	s_cbranch_execz .Lrt0_rest
	s_waitcnt vmcnt(0)
	v_pk_add_f32 v[48:49], v[48:49], v[50:51]
	v_pk_add_f32 v[52:53], v[52:53], v[54:55]
	v_pk_add_f32 v[56:57], v[56:57], v[58:59]
	v_pk_add_f32 v[60:61], v[60:61], v[62:63]
	v_pk_add_f32 v[48:49], v[48:49], v[52:53]
	v_pk_add_f32 v[56:57], v[56:57], v[60:61]
	v_pk_add_f32 v[48:49], v[48:49], v[56:57]
	s_nop 0
	v_add_f32_e32 v3, v48, v49
	v_fmamk_f32 v3, v3, 0x3a800000, v233
	v_rsq_f32_e32 v3, v3
	s_nop 0
	ds_write_b32 v2, v3
	s_cmp_lt_u32 s28, 2
	s_cbranch_scc1 .Lrt0_rest
	v_pk_add_f32 v[64:65], v[64:65], v[66:67]
	v_pk_add_f32 v[68:69], v[68:69], v[70:71]
	v_pk_add_f32 v[72:73], v[72:73], v[74:75]
	v_pk_add_f32 v[76:77], v[76:77], v[78:79]
	v_pk_add_f32 v[64:65], v[64:65], v[68:69]
	v_pk_add_f32 v[72:73], v[72:73], v[76:77]
	v_pk_add_f32 v[64:65], v[64:65], v[72:73]
	s_nop 0
	v_add_f32_e32 v3, v64, v65
	v_fmamk_f32 v3, v3, 0x3a800000, v233
	v_rsq_f32_e32 v3, v3
	s_nop 0
	ds_write_b32 v2, v3 offset:1024
	s_cmp_lt_u32 s28, 3
	s_cbranch_scc1 .Lrt0_rest
	v_pk_add_f32 v[100:101], v[100:101], v[102:103]
	v_pk_add_f32 v[104:105], v[104:105], v[106:107]
	v_pk_add_f32 v[108:109], v[108:109], v[110:111]
	v_pk_add_f32 v[112:113], v[112:113], v[114:115]
	v_pk_add_f32 v[100:101], v[100:101], v[104:105]
	v_pk_add_f32 v[108:109], v[108:109], v[112:113]
	v_pk_add_f32 v[100:101], v[100:101], v[108:109]
	s_nop 0
	v_add_f32_e32 v3, v100, v101
	v_fmamk_f32 v3, v3, 0x3a800000, v233
	v_rsq_f32_e32 v3, v3
	s_nop 0
	ds_write_b32 v2, v3 offset:2048
	s_cmp_lt_u32 s28, 4
	s_cbranch_scc1 .Lrt0_rest
	v_pk_add_f32 v[132:133], v[132:133], v[134:135]
	v_pk_add_f32 v[136:137], v[136:137], v[138:139]
	v_pk_add_f32 v[140:141], v[140:141], v[142:143]
	v_pk_add_f32 v[144:145], v[144:145], v[146:147]
	v_pk_add_f32 v[132:133], v[132:133], v[136:137]
	v_pk_add_f32 v[140:141], v[140:141], v[144:145]
	v_pk_add_f32 v[132:133], v[132:133], v[140:141]
	s_nop 0
	v_add_f32_e32 v3, v132, v133
	v_fmamk_f32 v3, v3, 0x3a800000, v233
	v_rsq_f32_e32 v3, v3
	s_nop 0
	ds_write_b32 v2, v3 offset:3072

; __device__ __forceinline__ int opaque_tid() { int t = threadIdx.x; asm volatile("" : "+v"(t)); return t; }
; #define LAS __attribute__((address_space(3)))
;     __host__ __device__ bool next(int i, Unit& u) const {
;         const long L = (long)i * G + c; if (L >= nwg) return false;
;         int wgid = (int)L; { const int q = nwg / NXCD, r = nwg % NXCD, xcd = wgid % NXCD, off = wgid / NXCD; wgid = (xcd < r ? xcd * (q + 1) : r * (q + 1) + (xcd - r) * q) + off; }
;         const int nig = wgm * nN, gid = wgid / nig, fm = gid * wgm, gsz = (nM - fm) < wgm ? (nM - fm) : wgm;
;         u.pm = fm + ((wgid % nig) % gsz); u.pn = (wgid % nig) / gsz; return true;
;     }
; template <class Sched> __device__ __forceinline__ void fill_rtab(LAS float* rtab, const Sched& S, const float* ss) {
;     pg8::Unit u; const int tix = pg8::opaque_tid();
; #pragma unroll 4
;     for (int i = 0; S.next(i, u) && i < 12; ++i) { if (tix < 256) { const f32x4* p = (const f32x4*)(ss + (size_t)(u.pm * 256 + tix) * 16);
;             const f32x4 a = p[0], b = p[1], c = p[2], d = p[3]; const float t = ((a[0] + a[1]) + (a[2] + a[3])) + ((b[0] + b[1]) + (b[2] + b[3])) + ((c[0] + c[1]) + (c[2] + c[3])) + ((d[0] + d[1]) + (d[2] + d[3]));
;             rtab[i * 256 + tix] = __builtin_amdgcn_rsqf(t * (1.0f / 1024.0f) + 1e-6f); } }
;     __syncthreads();
; }
.Lrt0_done:
	s_and_b64 vcc, exec, s[0:1]
	s_cbranch_vccnz .LBB0_317
	s_add_i32 s10, s10, 4
	v_readlane_b32 s0, v255, 25
	v_readlane_b32 s1, v255, 26
	s_add_u32 s12, s12, s0
	s_addc_u32 s13, s13, s1
	v_add_u32_e32 v2, 0x1000, v2
.LBB0_297:
	s_mov_b32 s28, 0
	v_mov_b64_e32 v[4:5], 0x280
	v_cmp_gt_i64_e32 vcc, s[12:13], v[164:165]
	v_cmp_lt_i64_e64 s[0:1], s[12:13], v[4:5]
	s_cbranch_vccnz .LBB0_299
	s_ashr_i32 s11, s12, 31
	s_lshr_b32 s11, s11, 29
	s_add_i32 s11, s12, s11
	s_ashr_i32 s14, s11, 3
	s_and_b32 s11, s11, -8
	s_sub_i32 s11, s12, s11
	s_cmp_lt_i32 s11, 0
	s_cselect_b32 s17, s43, 0x50
	s_mul_i32 s11, s11, s17
	s_add_i32 s11, s11, s14
	s_mul_hi_i32 s14, s11, 0x66666667
	s_lshr_b32 s17, s14, 31
	s_ashr_i32 s14, s14, 3
	s_add_i32 s14, s14, s17
	s_lshl_b32 s17, s14, 2
	s_sub_i32 s20, 0x80, s17
	s_min_i32 s20, s20, 4
	s_abs_i32 s20, s20
	v_cvt_f32_u32_e32 v3, s20
	s_sub_i32 s21, 0, s20
	s_mul_i32 s14, s14, 20
	s_sub_i32 s11, s11, s14
	v_rcp_iflag_f32_e32 v3, v3
	s_ashr_i32 s14, s11, 31
	s_abs_i32 s11, s11
	v_mul_f32_e32 v3, 0x4f7ffffe, v3
	v_cvt_u32_f32_e32 v3, v3
	s_nop 0
	v_readfirstlane_b32 s22, v3
	s_mul_i32 s21, s21, s22
	s_mul_hi_u32 s21, s22, s21
	s_add_i32 s22, s22, s21
	s_mul_hi_u32 s21, s11, s22
	s_mul_i32 s21, s21, s20
	s_sub_i32 s11, s11, s21
	s_sub_i32 s21, s11, s20
	s_cmp_ge_u32 s11, s20
	s_cselect_b32 s11, s21, s11
	s_sub_i32 s21, s11, s20
	s_cmp_ge_u32 s11, s20
	s_cselect_b32 s11, s21, s11
	s_xor_b32 s11, s11, s14
	s_sub_i32 s11, s11, s14
	s_add_i32 s11, s17, s11
.LBB0_299:
	s_cmp_lt_u32 s10, 12
	s_cselect_b64 s[20:21], -1, 0
	s_and_b64 s[0:1], s[0:1], s[20:21]
	s_andn2_b64 vcc, exec, s[0:1]
	s_mov_b64 s[0:1], -1
	s_cbranch_vccnz .LBB0_296
	s_and_saveexec_b64 s[0:1], s[4:5]
	s_cbranch_execz .LBB0_302
	v_lshl_add_u32 v48, s11, 8, v0
	v_ashrrev_i32_e32 v49, 31, v48
	v_lshlrev_b64 v[48:49], 6, v[48:49]
	v_lshl_add_u64 v[60:61], s[6:7], 0, v[48:49]
	global_load_dwordx4 v[48:51], v[60:61], off offset:48
	global_load_dwordx4 v[52:55], v[60:61], off offset:32
	global_load_dwordx4 v[56:59], v[60:61], off offset:16
	s_nop 0
	global_load_dwordx4 v[60:63], v[60:61], off
	s_mov_b32 s28, 1

; __device__ __forceinline__ int opaque_tid() { int t = threadIdx.x; asm volatile("" : "+v"(t)); return t; }
; #define LAS __attribute__((address_space(3)))
; template <class Sched> __device__ __forceinline__ void fill_rtab(LAS float* rtab, const Sched& S, const float* ss) {
;     pg8::Unit u; const int tix = pg8::opaque_tid();
; #pragma unroll 4
;     for (int i = 0; S.next(i, u) && i < 12; ++i) { if (tix < 256) { const f32x4* p = (const f32x4*)(ss + (size_t)(u.pm * 256 + tix) * 16);
;             const f32x4 a = p[0], b = p[1], c = p[2], d = p[3]; const float t = ((a[0] + a[1]) + (a[2] + a[3])) + ((b[0] + b[1]) + (b[2] + b[3])) + ((c[0] + c[1]) + (c[2] + c[3])) + ((d[0] + d[1]) + (d[2] + d[3]));
;             rtab[i * 256 + tix] = __builtin_amdgcn_rsqf(t * (1.0f / 1024.0f) + 1e-6f); } }
.LBB0_304:
	s_andn2_b64 vcc, exec, s[0:1]
	s_mov_b64 s[0:1], -1
	s_cbranch_vccnz .LBB0_296
	s_and_saveexec_b64 s[0:1], s[4:5]
	s_cbranch_execz .LBB0_307
	v_lshl_add_u32 v64, s11, 8, v0
	v_ashrrev_i32_e32 v65, 31, v64
	v_lshlrev_b64 v[64:65], 6, v[64:65]
	v_lshl_add_u64 v[76:77], s[6:7], 0, v[64:65]
	global_load_dwordx4 v[64:67], v[76:77], off offset:48
	global_load_dwordx4 v[68:71], v[76:77], off offset:32
	global_load_dwordx4 v[72:75], v[76:77], off offset:16
	s_nop 0
	global_load_dwordx4 v[76:79], v[76:77], off
	s_mov_b32 s28, 2

; __device__ __forceinline__ int opaque_tid() { int t = threadIdx.x; asm volatile("" : "+v"(t)); return t; }
; #define LAS __attribute__((address_space(3)))
; template <class Sched> __device__ __forceinline__ void fill_rtab(LAS float* rtab, const Sched& S, const float* ss) {
;     pg8::Unit u; const int tix = pg8::opaque_tid();
; #pragma unroll 4
;     for (int i = 0; S.next(i, u) && i < 12; ++i) { if (tix < 256) { const f32x4* p = (const f32x4*)(ss + (size_t)(u.pm * 256 + tix) * 16);
;             const f32x4 a = p[0], b = p[1], c = p[2], d = p[3]; const float t = ((a[0] + a[1]) + (a[2] + a[3])) + ((b[0] + b[1]) + (b[2] + b[3])) + ((c[0] + c[1]) + (c[2] + c[3])) + ((d[0] + d[1]) + (d[2] + d[3]));
;             rtab[i * 256 + tix] = __builtin_amdgcn_rsqf(t * (1.0f / 1024.0f) + 1e-6f); } }
.LBB0_309:
	s_andn2_b64 vcc, exec, s[0:1]
	s_mov_b64 s[0:1], -1
	s_cbranch_vccnz .LBB0_296
	s_and_saveexec_b64 s[0:1], s[4:5]
	s_cbranch_execz .LBB0_312
	v_lshl_add_u32 v100, s11, 8, v0
	v_ashrrev_i32_e32 v101, 31, v100
	v_lshlrev_b64 v[100:101], 6, v[100:101]
	v_lshl_add_u64 v[112:113], s[6:7], 0, v[100:101]
	global_load_dwordx4 v[100:103], v[112:113], off offset:48
	global_load_dwordx4 v[104:107], v[112:113], off offset:32
	global_load_dwordx4 v[108:111], v[112:113], off offset:16
	s_nop 0
	global_load_dwordx4 v[112:115], v[112:113], off
	s_mov_b32 s28, 3

; __device__ __forceinline__ int opaque_tid() { int t = threadIdx.x; asm volatile("" : "+v"(t)); return t; }
; #define LAS __attribute__((address_space(3)))
; template <class Sched> __device__ __forceinline__ void fill_rtab(LAS float* rtab, const Sched& S, const float* ss) {
;     pg8::Unit u; const int tix = pg8::opaque_tid();
; #pragma unroll 4
;     for (int i = 0; S.next(i, u) && i < 12; ++i) { if (tix < 256) { const f32x4* p = (const f32x4*)(ss + (size_t)(u.pm * 256 + tix) * 16);
;             const f32x4 a = p[0], b = p[1], c = p[2], d = p[3]; const float t = ((a[0] + a[1]) + (a[2] + a[3])) + ((b[0] + b[1]) + (b[2] + b[3])) + ((c[0] + c[1]) + (c[2] + c[3])) + ((d[0] + d[1]) + (d[2] + d[3]));
;             rtab[i * 256 + tix] = __builtin_amdgcn_rsqf(t * (1.0f / 1024.0f) + 1e-6f); } }
.LBB0_314:
	s_andn2_b64 vcc, exec, s[0:1]
	s_mov_b64 s[0:1], -1
	s_cbranch_vccnz .LBB0_296
	s_and_saveexec_b64 s[0:1], s[4:5]
	s_cbranch_execz .LBB0_295
	v_lshl_add_u32 v132, s11, 8, v0
	v_ashrrev_i32_e32 v133, 31, v132
	v_lshlrev_b64 v[132:133], 6, v[132:133]
	v_lshl_add_u64 v[144:145], s[6:7], 0, v[132:133]
	global_load_dwordx4 v[132:135], v[144:145], off offset:48
	global_load_dwordx4 v[136:139], v[144:145], off offset:32
	global_load_dwordx4 v[140:143], v[144:145], off offset:16
	s_nop 0
	global_load_dwordx4 v[144:147], v[144:145], off
	s_mov_b32 s28, 4
	s_branch .LBB0_295

; __device__ __forceinline__ int opaque_tid() { int t = threadIdx.x; asm volatile("" : "+v"(t)); return t; }
; #define LAS __attribute__((address_space(3)))
;     __host__ __device__ bool next(int i, Unit& u) const {
;         const long L = (long)i * G + c; if (L >= nwg) return false;
;         int wgid = (int)L; { const int q = nwg / NXCD, r = nwg % NXCD, xcd = wgid % NXCD, off = wgid / NXCD; wgid = (xcd < r ? xcd * (q + 1) : r * (q + 1) + (xcd - r) * q) + off; }
;         const int nig = wgm * nN, gid = wgid / nig, fm = gid * wgm, gsz = (nM - fm) < wgm ? (nM - fm) : wgm;
;         u.pm = fm + ((wgid % nig) % gsz); u.pn = (wgid % nig) / gsz; return true;
;     }
; template <class Sched> __device__ __forceinline__ void fill_rtab(LAS float* rtab, const Sched& S, const float* ss) {
;     pg8::Unit u; const int tix = pg8::opaque_tid();
; #pragma unroll 4
;     for (int i = 0; S.next(i, u) && i < 12; ++i) { if (tix < 256) { const f32x4* p = (const f32x4*)(ss + (size_t)(u.pm * 256 + tix) * 16);
;             const f32x4 a = p[0], b = p[1], c = p[2], d = p[3]; const float t = ((a[0] + a[1]) + (a[2] + a[3])) + ((b[0] + b[1]) + (b[2] + b[3])) + ((c[0] + c[1]) + (c[2] + c[3])) + ((d[0] + d[1]) + (d[2] + d[3]));
;             rtab[i * 256 + tix] = __builtin_amdgcn_rsqf(t * (1.0f / 1024.0f) + 1e-6f); } }
;     __syncthreads();
; }
.Lrt1_done:
	s_and_b64 vcc, exec, s[0:1]
	s_cbranch_vccnz .LBB0_398
	s_add_i32 s14, s14, 4
	v_readlane_b32 s0, v255, 25
	v_readlane_b32 s1, v255, 26
	s_add_u32 s12, s12, s0
	s_addc_u32 s13, s13, s1
	v_add_u32_e32 v2, 0x1000, v2
.LBB0_378:
	s_mov_b32 s28, 0
	v_cmp_gt_i64_e32 vcc, s[12:13], v[168:169]
	v_cmp_lt_i64_e64 s[0:1], s[12:13], v[166:167]
	s_cbranch_vccnz .LBB0_380
	s_ashr_i32 s15, s12, 31
	s_lshr_b32 s15, s15, 29
	s_add_i32 s15, s12, s15
	s_ashr_i32 s16, s15, 3
	s_and_b32 s15, s15, -8
	s_sub_i32 s15, s12, s15
	s_cmp_lt_i32 s15, 0
	s_cselect_b32 s17, s36, 0xc0
	s_mul_i32 s15, s15, s17
	s_add_i32 s15, s15, s16
	s_mul_hi_i32 s16, s15, 0x2aaaaaab
	s_lshr_b32 s17, s16, 31
	s_ashr_i32 s16, s16, 3
	s_add_i32 s16, s16, s17
	s_lshl_b32 s17, s16, 2
	s_sub_i32 s20, 0x80, s17
	s_min_i32 s20, s20, 4
	s_abs_i32 s20, s20
	v_cvt_f32_u32_e32 v3, s20
	s_sub_i32 s21, 0, s20
	s_mul_i32 s16, s16, 48
	s_sub_i32 s15, s15, s16
	v_rcp_iflag_f32_e32 v3, v3
	s_ashr_i32 s16, s15, 31
	s_abs_i32 s15, s15
	v_mul_f32_e32 v3, 0x4f7ffffe, v3
	v_cvt_u32_f32_e32 v3, v3
	s_nop 0
	v_readfirstlane_b32 s22, v3
	s_mul_i32 s21, s21, s22
	s_mul_hi_u32 s21, s22, s21
	s_add_i32 s22, s22, s21
	s_mul_hi_u32 s21, s15, s22
	s_mul_i32 s21, s21, s20
	s_sub_i32 s15, s15, s21
	s_sub_i32 s21, s15, s20
	s_cmp_ge_u32 s15, s20
	s_cselect_b32 s15, s21, s15
	s_sub_i32 s21, s15, s20
	s_cmp_ge_u32 s15, s20
	s_cselect_b32 s15, s21, s15
	s_xor_b32 s15, s15, s16
	s_sub_i32 s15, s15, s16
	s_add_i32 s15, s17, s15
.LBB0_380:
	s_cmp_lt_u32 s14, 12
	s_cselect_b64 s[16:17], -1, 0
	s_and_b64 s[0:1], s[0:1], s[16:17]
	s_andn2_b64 vcc, exec, s[0:1]
	s_mov_b64 s[0:1], -1
	s_cbranch_vccnz .LBB0_377
	s_and_saveexec_b64 s[0:1], s[4:5]
	s_cbranch_execz .LBB0_383
	v_lshl_add_u32 v48, s15, 8, v0
	v_ashrrev_i32_e32 v49, 31, v48
	v_lshlrev_b64 v[48:49], 6, v[48:49]
	v_lshl_add_u64 v[60:61], s[6:7], 0, v[48:49]
	global_load_dwordx4 v[48:51], v[60:61], off offset:48
	global_load_dwordx4 v[52:55], v[60:61], off offset:32
	global_load_dwordx4 v[56:59], v[60:61], off offset:16
	s_nop 0
	global_load_dwordx4 v[60:63], v[60:61], off
	s_mov_b32 s28, 1

; __device__ __forceinline__ int opaque_tid() { int t = threadIdx.x; asm volatile("" : "+v"(t)); return t; }
; #define LAS __attribute__((address_space(3)))
; template <class Sched> __device__ __forceinline__ void fill_rtab(LAS float* rtab, const Sched& S, const float* ss) {
;     pg8::Unit u; const int tix = pg8::opaque_tid();
; #pragma unroll 4
;     for (int i = 0; S.next(i, u) && i < 12; ++i) { if (tix < 256) { const f32x4* p = (const f32x4*)(ss + (size_t)(u.pm * 256 + tix) * 16);
;             const f32x4 a = p[0], b = p[1], c = p[2], d = p[3]; const float t = ((a[0] + a[1]) + (a[2] + a[3])) + ((b[0] + b[1]) + (b[2] + b[3])) + ((c[0] + c[1]) + (c[2] + c[3])) + ((d[0] + d[1]) + (d[2] + d[3]));
;             rtab[i * 256 + tix] = __builtin_amdgcn_rsqf(t * (1.0f / 1024.0f) + 1e-6f); } }
.LBB0_385:
	s_andn2_b64 vcc, exec, s[0:1]
	s_mov_b64 s[0:1], -1
	s_cbranch_vccnz .LBB0_377
	s_and_saveexec_b64 s[0:1], s[4:5]
	s_cbranch_execz .LBB0_388
	v_lshl_add_u32 v64, s15, 8, v0
	v_ashrrev_i32_e32 v65, 31, v64
	v_lshlrev_b64 v[64:65], 6, v[64:65]
	v_lshl_add_u64 v[76:77], s[6:7], 0, v[64:65]
	global_load_dwordx4 v[64:67], v[76:77], off offset:48
	global_load_dwordx4 v[68:71], v[76:77], off offset:32
	global_load_dwordx4 v[72:75], v[76:77], off offset:16
	s_nop 0
	global_load_dwordx4 v[76:79], v[76:77], off
	s_mov_b32 s28, 2

; __device__ __forceinline__ int opaque_tid() { int t = threadIdx.x; asm volatile("" : "+v"(t)); return t; }
; #define LAS __attribute__((address_space(3)))
; template <class Sched> __device__ __forceinline__ void fill_rtab(LAS float* rtab, const Sched& S, const float* ss) {
;     pg8::Unit u; const int tix = pg8::opaque_tid();
; #pragma unroll 4
;     for (int i = 0; S.next(i, u) && i < 12; ++i) { if (tix < 256) { const f32x4* p = (const f32x4*)(ss + (size_t)(u.pm * 256 + tix) * 16);
;             const f32x4 a = p[0], b = p[1], c = p[2], d = p[3]; const float t = ((a[0] + a[1]) + (a[2] + a[3])) + ((b[0] + b[1]) + (b[2] + b[3])) + ((c[0] + c[1]) + (c[2] + c[3])) + ((d[0] + d[1]) + (d[2] + d[3]));
;             rtab[i * 256 + tix] = __builtin_amdgcn_rsqf(t * (1.0f / 1024.0f) + 1e-6f); } }
.LBB0_390:
	s_andn2_b64 vcc, exec, s[0:1]
	s_mov_b64 s[0:1], -1
	s_cbranch_vccnz .LBB0_377
	s_and_saveexec_b64 s[0:1], s[4:5]
	s_cbranch_execz .LBB0_393
	v_lshl_add_u32 v100, s15, 8, v0
	v_ashrrev_i32_e32 v101, 31, v100
	v_lshlrev_b64 v[100:101], 6, v[100:101]
	v_lshl_add_u64 v[112:113], s[6:7], 0, v[100:101]
	global_load_dwordx4 v[100:103], v[112:113], off offset:48
	global_load_dwordx4 v[104:107], v[112:113], off offset:32
	global_load_dwordx4 v[108:111], v[112:113], off offset:16
	s_nop 0
	global_load_dwordx4 v[112:115], v[112:113], off
	s_mov_b32 s28, 3

; __device__ __forceinline__ int opaque_tid() { int t = threadIdx.x; asm volatile("" : "+v"(t)); return t; }
; #define LAS __attribute__((address_space(3)))
; template <class Sched> __device__ __forceinline__ void fill_rtab(LAS float* rtab, const Sched& S, const float* ss) {
;     pg8::Unit u; const int tix = pg8::opaque_tid();
; #pragma unroll 4
;     for (int i = 0; S.next(i, u) && i < 12; ++i) { if (tix < 256) { const f32x4* p = (const f32x4*)(ss + (size_t)(u.pm * 256 + tix) * 16);
;             const f32x4 a = p[0], b = p[1], c = p[2], d = p[3]; const float t = ((a[0] + a[1]) + (a[2] + a[3])) + ((b[0] + b[1]) + (b[2] + b[3])) + ((c[0] + c[1]) + (c[2] + c[3])) + ((d[0] + d[1]) + (d[2] + d[3]));
;             rtab[i * 256 + tix] = __builtin_amdgcn_rsqf(t * (1.0f / 1024.0f) + 1e-6f); } }
.LBB0_395:
	s_andn2_b64 vcc, exec, s[0:1]
	s_mov_b64 s[0:1], -1
	s_cbranch_vccnz .LBB0_377
	s_and_saveexec_b64 s[0:1], s[4:5]
	s_cbranch_execz .LBB0_376
	v_lshl_add_u32 v132, s15, 8, v0
	v_ashrrev_i32_e32 v133, 31, v132
	v_lshlrev_b64 v[132:133], 6, v[132:133]
	v_lshl_add_u64 v[144:145], s[6:7], 0, v[132:133]
	global_load_dwordx4 v[132:135], v[144:145], off offset:48
	global_load_dwordx4 v[136:139], v[144:145], off offset:32
	global_load_dwordx4 v[140:143], v[144:145], off offset:16
	s_nop 0
	global_load_dwordx4 v[144:147], v[144:145], off
	s_mov_b32 s28, 4
	s_branch .LBB0_376

; __device__ __forceinline__ int opaque_tid() { int t = threadIdx.x; asm volatile("" : "+v"(t)); return t; }
; #define LAS __attribute__((address_space(3)))
; template <class Sched> __device__ __forceinline__ void fill_rtab(LAS float* rtab, const Sched& S, const float* ss) {
;     pg8::Unit u; const int tix = pg8::opaque_tid();
; #pragma unroll 4
;     for (int i = 0; S.next(i, u) && i < 12; ++i) { if (tix < 256) { const f32x4* p = (const f32x4*)(ss + (size_t)(u.pm * 256 + tix) * 16);
;             const f32x4 a = p[0], b = p[1], c = p[2], d = p[3]; const float t = ((a[0] + a[1]) + (a[2] + a[3])) + ((b[0] + b[1]) + (b[2] + b[3])) + ((c[0] + c[1]) + (c[2] + c[3])) + ((d[0] + d[1]) + (d[2] + d[3]));
;             rtab[i * 256 + tix] = __builtin_amdgcn_rsqf(t * (1.0f / 1024.0f) + 1e-6f); } }
;     __syncthreads();
; }
.LBB0_852:
	s_cmp_eq_u32 s28, 0
	s_cbranch_scc1 .Lrt2_done
	s_and_saveexec_b64 s[40:41], s[6:7]
	s_cbranch_execz .Lrt2_rest
	s_waitcnt vmcnt(0)
	v_pk_add_f32 v[48:49], v[48:49], v[50:51]
	v_pk_add_f32 v[52:53], v[52:53], v[54:55]
	v_pk_add_f32 v[56:57], v[56:57], v[58:59]
	v_pk_add_f32 v[60:61], v[60:61], v[62:63]
	v_pk_add_f32 v[48:49], v[48:49], v[52:53]
	v_pk_add_f32 v[56:57], v[56:57], v[60:61]
	v_pk_add_f32 v[48:49], v[48:49], v[56:57]
	s_nop 0
	v_add_f32_e32 v3, v48, v49
	v_fmamk_f32 v3, v3, 0x3a800000, v233
	v_rsq_f32_e32 v3, v3
	s_nop 0
	ds_write_b32 v2, v3
	s_cmp_lt_u32 s28, 2
	s_cbranch_scc1 .Lrt2_rest
	v_pk_add_f32 v[64:65], v[64:65], v[66:67]
	v_pk_add_f32 v[68:69], v[68:69], v[70:71]
	v_pk_add_f32 v[72:73], v[72:73], v[74:75]
	v_pk_add_f32 v[76:77], v[76:77], v[78:79]
	v_pk_add_f32 v[64:65], v[64:65], v[68:69]
	v_pk_add_f32 v[72:73], v[72:73], v[76:77]
	v_pk_add_f32 v[64:65], v[64:65], v[72:73]
	s_nop 0
	v_add_f32_e32 v3, v64, v65
	v_fmamk_f32 v3, v3, 0x3a800000, v233
	v_rsq_f32_e32 v3, v3
	s_nop 0
	ds_write_b32 v2, v3 offset:1024
	s_cmp_lt_u32 s28, 3
	s_cbranch_scc1 .Lrt2_rest
	v_pk_add_f32 v[100:101], v[100:101], v[102:103]
	v_pk_add_f32 v[104:105], v[104:105], v[106:107]
	v_pk_add_f32 v[108:109], v[108:109], v[110:111]
	v_pk_add_f32 v[112:113], v[112:113], v[114:115]
	v_pk_add_f32 v[100:101], v[100:101], v[104:105]
	v_pk_add_f32 v[108:109], v[108:109], v[112:113]
	v_pk_add_f32 v[100:101], v[100:101], v[108:109]
	s_nop 0
	v_add_f32_e32 v3, v100, v101
	v_fmamk_f32 v3, v3, 0x3a800000, v233
	v_rsq_f32_e32 v3, v3
	s_nop 0
	ds_write_b32 v2, v3 offset:2048
	s_cmp_lt_u32 s28, 4
	s_cbranch_scc1 .Lrt2_rest
	v_pk_add_f32 v[132:133], v[132:133], v[134:135]
	v_pk_add_f32 v[136:137], v[136:137], v[138:139]
	v_pk_add_f32 v[140:141], v[140:141], v[142:143]
	v_pk_add_f32 v[144:145], v[144:145], v[146:147]
	v_pk_add_f32 v[132:133], v[132:133], v[136:137]
	v_pk_add_f32 v[140:141], v[140:141], v[144:145]
	v_pk_add_f32 v[132:133], v[132:133], v[140:141]
	s_nop 0
	v_add_f32_e32 v3, v132, v133
	v_fmamk_f32 v3, v3, 0x3a800000, v233
	v_rsq_f32_e32 v3, v3
	s_nop 0
	ds_write_b32 v2, v3 offset:3072

; __device__ __forceinline__ int opaque_tid() { int t = threadIdx.x; asm volatile("" : "+v"(t)); return t; }
; #define LAS __attribute__((address_space(3)))
;     __host__ __device__ bool next(int i, Unit& u) const {
;         const long L = (long)i * G + c; if (L >= nwg) return false;
;         int wgid = (int)L; { const int q = nwg / NXCD, r = nwg % NXCD, xcd = wgid % NXCD, off = wgid / NXCD; wgid = (xcd < r ? xcd * (q + 1) : r * (q + 1) + (xcd - r) * q) + off; }
;         const int nig = wgm * nN, gid = wgid / nig, fm = gid * wgm, gsz = (nM - fm) < wgm ? (nM - fm) : wgm;
;         u.pm = fm + ((wgid % nig) % gsz); u.pn = (wgid % nig) / gsz; return true;
;     }
; template <class Sched> __device__ __forceinline__ void fill_rtab(LAS float* rtab, const Sched& S, const float* ss) {
;     pg8::Unit u; const int tix = pg8::opaque_tid();
; #pragma unroll 4
;     for (int i = 0; S.next(i, u) && i < 12; ++i) { if (tix < 256) { const f32x4* p = (const f32x4*)(ss + (size_t)(u.pm * 256 + tix) * 16);
;             const f32x4 a = p[0], b = p[1], c = p[2], d = p[3]; const float t = ((a[0] + a[1]) + (a[2] + a[3])) + ((b[0] + b[1]) + (b[2] + b[3])) + ((c[0] + c[1]) + (c[2] + c[3])) + ((d[0] + d[1]) + (d[2] + d[3]));
;             rtab[i * 256 + tix] = __builtin_amdgcn_rsqf(t * (1.0f / 1024.0f) + 1e-6f); } }
;     __syncthreads();
; }
.Lrt2_done:
	s_and_b64 vcc, exec, s[0:1]
	s_cbranch_vccnz .LBB0_889
	s_add_i32 s14, s14, 4
	v_readlane_b32 s0, v255, 25
	v_readlane_b32 s1, v255, 26
	s_add_u32 s10, s10, s0
	s_addc_u32 s11, s11, s1
	v_add_u32_e32 v2, 0x1000, v2
.LBB0_853:
	s_mov_b32 s28, 0
	v_cmp_gt_i64_e32 vcc, s[10:11], v[176:177]
	v_cmp_lt_i64_e64 s[0:1], s[10:11], v[174:175]
	s_cbranch_vccnz .LBB0_859
	s_ashr_i32 s4, s10, 31
	s_lshr_b32 s4, s4, 29
	s_add_i32 s4, s10, s4
	s_and_b32 s5, s4, -8
	s_sub_i32 s5, s10, s5
	s_cmp_gt_i32 s5, -1
	s_mov_b64 s[12:13], -1
	s_cbranch_scc0 .LBB0_856
	s_lshl_b32 s15, s5, 5
	s_mov_b64 s[12:13], 0

; __device__ __forceinline__ int opaque_tid() { int t = threadIdx.x; asm volatile("" : "+v"(t)); return t; }
; #define LAS __attribute__((address_space(3)))
; template <class Sched> __device__ __forceinline__ void fill_rtab(LAS float* rtab, const Sched& S, const float* ss) {
;     pg8::Unit u; const int tix = pg8::opaque_tid();
; #pragma unroll 4
;     for (int i = 0; S.next(i, u) && i < 12; ++i) { if (tix < 256) { const f32x4* p = (const f32x4*)(ss + (size_t)(u.pm * 256 + tix) * 16);
;             const f32x4 a = p[0], b = p[1], c = p[2], d = p[3]; const float t = ((a[0] + a[1]) + (a[2] + a[3])) + ((b[0] + b[1]) + (b[2] + b[3])) + ((c[0] + c[1]) + (c[2] + c[3])) + ((d[0] + d[1]) + (d[2] + d[3]));
;             rtab[i * 256 + tix] = __builtin_amdgcn_rsqf(t * (1.0f / 1024.0f) + 1e-6f); } }
.LBB0_859:
	s_cmp_lt_u32 s14, 12
	s_cselect_b64 s[12:13], -1, 0
	s_and_b64 s[0:1], s[0:1], s[12:13]
	s_andn2_b64 vcc, exec, s[0:1]
	s_mov_b64 s[0:1], -1
	s_cbranch_vccnz .LBB0_852
	s_and_saveexec_b64 s[0:1], s[6:7]
	s_cbranch_execz .LBB0_862
	v_lshl_add_u32 v48, s4, 8, v0
	v_ashrrev_i32_e32 v49, 31, v48
	v_lshlrev_b64 v[48:49], 6, v[48:49]
	v_lshl_add_u64 v[60:61], s[8:9], 0, v[48:49]
	global_load_dwordx4 v[48:51], v[60:61], off offset:48
	global_load_dwordx4 v[52:55], v[60:61], off offset:32
	global_load_dwordx4 v[56:59], v[60:61], off offset:16
	s_nop 0
	global_load_dwordx4 v[60:63], v[60:61], off
	s_mov_b32 s28, 1

; __device__ __forceinline__ int opaque_tid() { int t = threadIdx.x; asm volatile("" : "+v"(t)); return t; }
; #define LAS __attribute__((address_space(3)))
; template <class Sched> __device__ __forceinline__ void fill_rtab(LAS float* rtab, const Sched& S, const float* ss) {
;     pg8::Unit u; const int tix = pg8::opaque_tid();
; #pragma unroll 4
;     for (int i = 0; S.next(i, u) && i < 12; ++i) { if (tix < 256) { const f32x4* p = (const f32x4*)(ss + (size_t)(u.pm * 256 + tix) * 16);
;             const f32x4 a = p[0], b = p[1], c = p[2], d = p[3]; const float t = ((a[0] + a[1]) + (a[2] + a[3])) + ((b[0] + b[1]) + (b[2] + b[3])) + ((c[0] + c[1]) + (c[2] + c[3])) + ((d[0] + d[1]) + (d[2] + d[3]));
;             rtab[i * 256 + tix] = __builtin_amdgcn_rsqf(t * (1.0f / 1024.0f) + 1e-6f); } }
.LBB0_868:
	s_andn2_b64 vcc, exec, s[0:1]
	s_mov_b64 s[0:1], -1
	s_cbranch_vccnz .LBB0_852
	s_and_saveexec_b64 s[0:1], s[6:7]
	s_cbranch_execz .LBB0_871
	v_lshl_add_u32 v64, s4, 8, v0
	v_ashrrev_i32_e32 v65, 31, v64
	v_lshlrev_b64 v[64:65], 6, v[64:65]
	v_lshl_add_u64 v[76:77], s[8:9], 0, v[64:65]
	global_load_dwordx4 v[64:67], v[76:77], off offset:48
	global_load_dwordx4 v[68:71], v[76:77], off offset:32
	global_load_dwordx4 v[72:75], v[76:77], off offset:16
	s_nop 0
	global_load_dwordx4 v[76:79], v[76:77], off
	s_mov_b32 s28, 2

; __device__ __forceinline__ int opaque_tid() { int t = threadIdx.x; asm volatile("" : "+v"(t)); return t; }
; #define LAS __attribute__((address_space(3)))
; template <class Sched> __device__ __forceinline__ void fill_rtab(LAS float* rtab, const Sched& S, const float* ss) {
;     pg8::Unit u; const int tix = pg8::opaque_tid();
; #pragma unroll 4
;     for (int i = 0; S.next(i, u) && i < 12; ++i) { if (tix < 256) { const f32x4* p = (const f32x4*)(ss + (size_t)(u.pm * 256 + tix) * 16);
;             const f32x4 a = p[0], b = p[1], c = p[2], d = p[3]; const float t = ((a[0] + a[1]) + (a[2] + a[3])) + ((b[0] + b[1]) + (b[2] + b[3])) + ((c[0] + c[1]) + (c[2] + c[3])) + ((d[0] + d[1]) + (d[2] + d[3]));
;             rtab[i * 256 + tix] = __builtin_amdgcn_rsqf(t * (1.0f / 1024.0f) + 1e-6f); } }
.LBB0_877:
	s_andn2_b64 vcc, exec, s[0:1]
	s_mov_b64 s[0:1], -1
	s_cbranch_vccnz .LBB0_852
	s_and_saveexec_b64 s[0:1], s[6:7]
	s_cbranch_execz .LBB0_880
	v_lshl_add_u32 v100, s4, 8, v0
	v_ashrrev_i32_e32 v101, 31, v100
	v_lshlrev_b64 v[100:101], 6, v[100:101]
	v_lshl_add_u64 v[112:113], s[8:9], 0, v[100:101]
	global_load_dwordx4 v[100:103], v[112:113], off offset:48
	global_load_dwordx4 v[104:107], v[112:113], off offset:32
	global_load_dwordx4 v[108:111], v[112:113], off offset:16
	s_nop 0
	global_load_dwordx4 v[112:115], v[112:113], off
	s_mov_b32 s28, 3

; __device__ __forceinline__ int opaque_tid() { int t = threadIdx.x; asm volatile("" : "+v"(t)); return t; }
; #define LAS __attribute__((address_space(3)))
; template <class Sched> __device__ __forceinline__ void fill_rtab(LAS float* rtab, const Sched& S, const float* ss) {
;     pg8::Unit u; const int tix = pg8::opaque_tid();
; #pragma unroll 4
;     for (int i = 0; S.next(i, u) && i < 12; ++i) { if (tix < 256) { const f32x4* p = (const f32x4*)(ss + (size_t)(u.pm * 256 + tix) * 16);
;             const f32x4 a = p[0], b = p[1], c = p[2], d = p[3]; const float t = ((a[0] + a[1]) + (a[2] + a[3])) + ((b[0] + b[1]) + (b[2] + b[3])) + ((c[0] + c[1]) + (c[2] + c[3])) + ((d[0] + d[1]) + (d[2] + d[3]));
;             rtab[i * 256 + tix] = __builtin_amdgcn_rsqf(t * (1.0f / 1024.0f) + 1e-6f); } }
.LBB0_886:
	s_andn2_b64 vcc, exec, s[0:1]
	s_mov_b64 s[0:1], -1
	s_cbranch_vccnz .LBB0_852
	s_and_saveexec_b64 s[0:1], s[6:7]
	s_cbranch_execz .LBB0_851
	v_lshl_add_u32 v132, s4, 8, v0
	v_ashrrev_i32_e32 v133, 31, v132
	v_lshlrev_b64 v[132:133], 6, v[132:133]
	v_lshl_add_u64 v[144:145], s[8:9], 0, v[132:133]
	global_load_dwordx4 v[132:135], v[144:145], off offset:48
	global_load_dwordx4 v[136:139], v[144:145], off offset:32
	global_load_dwordx4 v[140:143], v[144:145], off offset:16
	s_nop 0
	global_load_dwordx4 v[144:147], v[144:145], off
	s_mov_b32 s28, 4
	s_branch .LBB0_851

; __device__ __forceinline__ int opaque_tid() { int t = threadIdx.x; asm volatile("" : "+v"(t)); return t; }
; #define LAS __attribute__((address_space(3)))
;     __host__ __device__ bool next(int i, Unit& u) const {
;         const long L = (long)i * G + c; if (L >= nwg) return false;
;         int wgid = (int)L; { const int q = nwg / NXCD, r = nwg % NXCD, xcd = wgid % NXCD, off = wgid / NXCD; wgid = (xcd < r ? xcd * (q + 1) : r * (q + 1) + (xcd - r) * q) + off; }
;         const int nig = wgm * nN, gid = wgid / nig, fm = gid * wgm, gsz = (nM - fm) < wgm ? (nM - fm) : wgm;
;         u.pm = fm + ((wgid % nig) % gsz); u.pn = (wgid % nig) / gsz; return true;
;     }
; template <class Sched> __device__ __forceinline__ void fill_rtab(LAS float* rtab, const Sched& S, const float* ss) {
;     pg8::Unit u; const int tix = pg8::opaque_tid();
; #pragma unroll 4
;     for (int i = 0; S.next(i, u) && i < 12; ++i) { if (tix < 256) { const f32x4* p = (const f32x4*)(ss + (size_t)(u.pm * 256 + tix) * 16);
;             const f32x4 a = p[0], b = p[1], c = p[2], d = p[3]; const float t = ((a[0] + a[1]) + (a[2] + a[3])) + ((b[0] + b[1]) + (b[2] + b[3])) + ((c[0] + c[1]) + (c[2] + c[3])) + ((d[0] + d[1]) + (d[2] + d[3]));
;             rtab[i * 256 + tix] = __builtin_amdgcn_rsqf(t * (1.0f / 1024.0f) + 1e-6f); } }
;     __syncthreads();
; }
.Lrt3_done:
	s_and_b64 vcc, exec, s[0:1]
	s_cbranch_vccnz .LBB0_1166
	s_add_i32 s12, s12, 4
	v_readlane_b32 s0, v255, 25
	v_readlane_b32 s1, v255, 26
	s_add_u32 s10, s10, s0
	s_addc_u32 s11, s11, s1
	v_add_u32_e32 v2, 0x1000, v2
.LBB0_1146:
	s_mov_b32 s28, 0
	v_cmp_gt_i64_e32 vcc, s[10:11], v[180:181]
	v_cmp_lt_i64_e64 s[0:1], s[10:11], v[178:179]
	s_cbranch_vccnz .LBB0_1148
	s_ashr_i32 s13, s10, 31
	s_lshr_b32 s13, s13, 29
	s_add_i32 s13, s10, s13
	s_ashr_i32 s14, s13, 3
	s_and_b32 s13, s13, -8
	s_sub_i32 s13, s10, s13
	s_cmp_lt_i32 s13, 0
	s_cselect_b32 s15, s63, 0x160
	s_mul_i32 s13, s13, s15
	s_add_i32 s13, s13, s14
	s_mul_hi_i32 s14, s13, 0x2e8ba2e9
	s_lshr_b32 s15, s14, 31
	s_ashr_i32 s14, s14, 4
	s_add_i32 s14, s14, s15
	s_lshl_b32 s15, s14, 2
	s_sub_i32 s16, 0x80, s15
	s_min_i32 s16, s16, 4
	s_abs_i32 s16, s16
	v_cvt_f32_u32_e32 v3, s16
	s_sub_i32 s17, 0, s16
	s_mulk_i32 s14, 0x58
	s_sub_i32 s13, s13, s14
	v_rcp_iflag_f32_e32 v3, v3
	s_ashr_i32 s14, s13, 31
	s_abs_i32 s13, s13
	v_mul_f32_e32 v3, 0x4f7ffffe, v3
	v_cvt_u32_f32_e32 v3, v3
	s_nop 0
	v_readfirstlane_b32 s20, v3
	s_mul_i32 s17, s17, s20
	s_mul_hi_u32 s17, s20, s17
	s_add_i32 s20, s20, s17
	s_mul_hi_u32 s17, s13, s20
	s_mul_i32 s17, s17, s16
	s_sub_i32 s13, s13, s17
	s_sub_i32 s17, s13, s16
	s_cmp_ge_u32 s13, s16
	s_cselect_b32 s13, s17, s13
	s_sub_i32 s17, s13, s16
	s_cmp_ge_u32 s13, s16
	s_cselect_b32 s13, s17, s13
	s_xor_b32 s13, s13, s14
	s_sub_i32 s13, s13, s14
	s_add_i32 s13, s15, s13
.LBB0_1148:
	s_cmp_lt_u32 s12, 12
	s_cselect_b64 s[14:15], -1, 0
	s_and_b64 s[0:1], s[0:1], s[14:15]
	s_andn2_b64 vcc, exec, s[0:1]
	s_mov_b64 s[0:1], -1
	s_cbranch_vccnz .LBB0_1145
	s_and_saveexec_b64 s[0:1], s[6:7]
	s_cbranch_execz .LBB0_1151
	v_lshl_add_u32 v48, s13, 8, v0
	v_ashrrev_i32_e32 v49, 31, v48
	v_lshlrev_b64 v[48:49], 6, v[48:49]
	v_lshl_add_u64 v[60:61], s[8:9], 0, v[48:49]
	global_load_dwordx4 v[48:51], v[60:61], off offset:48
	global_load_dwordx4 v[52:55], v[60:61], off offset:32
	global_load_dwordx4 v[56:59], v[60:61], off offset:16
	s_nop 0
	global_load_dwordx4 v[60:63], v[60:61], off
	s_mov_b32 s28, 1

; __device__ __forceinline__ int opaque_tid() { int t = threadIdx.x; asm volatile("" : "+v"(t)); return t; }
; #define LAS __attribute__((address_space(3)))
; template <class Sched> __device__ __forceinline__ void fill_rtab(LAS float* rtab, const Sched& S, const float* ss) {
;     pg8::Unit u; const int tix = pg8::opaque_tid();
; #pragma unroll 4
;     for (int i = 0; S.next(i, u) && i < 12; ++i) { if (tix < 256) { const f32x4* p = (const f32x4*)(ss + (size_t)(u.pm * 256 + tix) * 16);
;             const f32x4 a = p[0], b = p[1], c = p[2], d = p[3]; const float t = ((a[0] + a[1]) + (a[2] + a[3])) + ((b[0] + b[1]) + (b[2] + b[3])) + ((c[0] + c[1]) + (c[2] + c[3])) + ((d[0] + d[1]) + (d[2] + d[3]));
;             rtab[i * 256 + tix] = __builtin_amdgcn_rsqf(t * (1.0f / 1024.0f) + 1e-6f); } }
.LBB0_1153:
	s_andn2_b64 vcc, exec, s[0:1]
	s_mov_b64 s[0:1], -1
	s_cbranch_vccnz .LBB0_1145
	s_and_saveexec_b64 s[0:1], s[6:7]
	s_cbranch_execz .LBB0_1156
	v_lshl_add_u32 v64, s13, 8, v0
	v_ashrrev_i32_e32 v65, 31, v64
	v_lshlrev_b64 v[64:65], 6, v[64:65]
	v_lshl_add_u64 v[76:77], s[8:9], 0, v[64:65]
	global_load_dwordx4 v[64:67], v[76:77], off offset:48
	global_load_dwordx4 v[68:71], v[76:77], off offset:32
	global_load_dwordx4 v[72:75], v[76:77], off offset:16
	s_nop 0
	global_load_dwordx4 v[76:79], v[76:77], off
	s_mov_b32 s28, 2

; __device__ __forceinline__ int opaque_tid() { int t = threadIdx.x; asm volatile("" : "+v"(t)); return t; }
; #define LAS __attribute__((address_space(3)))
; template <class Sched> __device__ __forceinline__ void fill_rtab(LAS float* rtab, const Sched& S, const float* ss) {
;     pg8::Unit u; const int tix = pg8::opaque_tid();
; #pragma unroll 4
;     for (int i = 0; S.next(i, u) && i < 12; ++i) { if (tix < 256) { const f32x4* p = (const f32x4*)(ss + (size_t)(u.pm * 256 + tix) * 16);
;             const f32x4 a = p[0], b = p[1], c = p[2], d = p[3]; const float t = ((a[0] + a[1]) + (a[2] + a[3])) + ((b[0] + b[1]) + (b[2] + b[3])) + ((c[0] + c[1]) + (c[2] + c[3])) + ((d[0] + d[1]) + (d[2] + d[3]));
;             rtab[i * 256 + tix] = __builtin_amdgcn_rsqf(t * (1.0f / 1024.0f) + 1e-6f); } }
.LBB0_1158:
	s_andn2_b64 vcc, exec, s[0:1]
	s_mov_b64 s[0:1], -1
	s_cbranch_vccnz .LBB0_1145
	s_and_saveexec_b64 s[0:1], s[6:7]
	s_cbranch_execz .LBB0_1161
	v_lshl_add_u32 v100, s13, 8, v0
	v_ashrrev_i32_e32 v101, 31, v100
	v_lshlrev_b64 v[100:101], 6, v[100:101]
	v_lshl_add_u64 v[112:113], s[8:9], 0, v[100:101]
	global_load_dwordx4 v[100:103], v[112:113], off offset:48
	global_load_dwordx4 v[104:107], v[112:113], off offset:32
	global_load_dwordx4 v[108:111], v[112:113], off offset:16
	s_nop 0
	global_load_dwordx4 v[112:115], v[112:113], off
	s_mov_b32 s28, 3

; __device__ __forceinline__ int opaque_tid() { int t = threadIdx.x; asm volatile("" : "+v"(t)); return t; }
; #define LAS __attribute__((address_space(3)))
; template <class Sched> __device__ __forceinline__ void fill_rtab(LAS float* rtab, const Sched& S, const float* ss) {
;     pg8::Unit u; const int tix = pg8::opaque_tid();
; #pragma unroll 4
;     for (int i = 0; S.next(i, u) && i < 12; ++i) { if (tix < 256) { const f32x4* p = (const f32x4*)(ss + (size_t)(u.pm * 256 + tix) * 16);
;             const f32x4 a = p[0], b = p[1], c = p[2], d = p[3]; const float t = ((a[0] + a[1]) + (a[2] + a[3])) + ((b[0] + b[1]) + (b[2] + b[3])) + ((c[0] + c[1]) + (c[2] + c[3])) + ((d[0] + d[1]) + (d[2] + d[3]));
;             rtab[i * 256 + tix] = __builtin_amdgcn_rsqf(t * (1.0f / 1024.0f) + 1e-6f); } }
.LBB0_1163:
	s_andn2_b64 vcc, exec, s[0:1]
	s_mov_b64 s[0:1], -1
	s_cbranch_vccnz .LBB0_1145
	s_and_saveexec_b64 s[0:1], s[6:7]
	s_cbranch_execz .LBB0_1144
	v_lshl_add_u32 v132, s13, 8, v0
	v_ashrrev_i32_e32 v133, 31, v132
	v_lshlrev_b64 v[132:133], 6, v[132:133]
	v_lshl_add_u64 v[144:145], s[8:9], 0, v[132:133]
	global_load_dwordx4 v[132:135], v[144:145], off offset:48
	global_load_dwordx4 v[136:139], v[144:145], off offset:32
	global_load_dwordx4 v[140:143], v[144:145], off offset:16
	s_nop 0
	global_load_dwordx4 v[144:147], v[144:145], off
	s_mov_b32 s28, 4
	s_branch .LBB0_1144
